# E12 + E8 (LDS-DMA addresses via SGPR base) combined
# baseline (speedup 1.0000x reference)
.LBB0_731:
	s_mov_b32 s44, s29
	s_mov_b32 s28, s25
	v_add_u32_e32 v195, s45, v190
	ds_read_b64_tr_b16 v[196:197], v195 offset:24576
	ds_read_b64_tr_b16 v[198:199], v195 offset:25088
	v_add_f32_e32 v88, v68, v69
	v_add_f32_e32 v88, v70, v88
	v_add_f32_e32 v88, v71, v88
	v_add_f32_e32 v88, v72, v88
	v_add_f32_e32 v88, v73, v88
	v_cvt_pk_bf16_f32 v152, v68, v69
	v_cvt_pk_bf16_f32 v153, v70, v71
	v_mfma_f32_32x32x16_bf16 v[100:115], v[84:87], v[160:163], 0
	ds_read_b64_tr_b16 v[68:69], v195 offset:28672
	ds_read_b64_tr_b16 v[70:71], v195 offset:29184
	v_add_f32_e32 v84, v74, v88
	v_add_f32_e32 v84, v75, v84
	v_add_f32_e32 v84, v76, v84
	v_add_f32_e32 v132, v77, v84
	v_mfma_f32_32x32x16_bf16 v[84:99], v[168:171], v[160:163], 0
	v_cvt_pk_bf16_f32 v154, v72, v73
	v_cvt_pk_bf16_f32 v155, v74, v75
	ds_read_b64_tr_b16 v[72:73], v195 offset:25600
	ds_read_b64_tr_b16 v[74:75], v195 offset:26112
	v_add_f32_e32 v132, v78, v132
	v_add_f32_e32 v132, v79, v132
	v_add_f32_e32 v132, v80, v132
	v_add_f32_e32 v132, v81, v132
	v_cvt_pk_bf16_f32 v148, v76, v77
	v_cvt_pk_bf16_f32 v149, v78, v79
	v_mfma_f32_32x32x16_bf16 v[100:115], v[172:175], v[156:159], v[100:115]
	ds_read_b64_tr_b16 v[76:77], v195 offset:29696
	ds_read_b64_tr_b16 v[78:79], v195 offset:30208
	v_mfma_f32_32x32x16_bf16 v[84:99], v[164:167], v[156:159], v[84:99]
	v_add_f32_e32 v132, v82, v132
	v_add_f32_e32 v132, v83, v132
	v_add_f32_e32 v132, v52, v132
	v_add_f32_e32 v132, v53, v132
	v_cvt_pk_bf16_f32 v150, v80, v81
	v_cvt_pk_bf16_f32 v151, v82, v83
	ds_read_b64_tr_b16 v[80:81], v195 offset:26624
	ds_read_b64_tr_b16 v[82:83], v195 offset:27136
	v_mfma_f32_32x32x16_bf16 v[100:115], v[128:131], v[144:147], v[100:115]
	v_add_f32_e32 v128, v54, v132
	v_add_f32_e32 v128, v55, v128
	v_add_f32_e32 v128, v56, v128
	v_add_f32_e32 v128, v57, v128
	v_cvt_pk_bf16_f32 v140, v52, v53
	v_cvt_pk_bf16_f32 v141, v54, v55
	ds_read_b64_tr_b16 v[52:53], v195 offset:30720
	ds_read_b64_tr_b16 v[54:55], v195 offset:31232
	v_mfma_f32_32x32x16_bf16 v[84:99], v[124:127], v[144:147], v[84:99]
	v_add_f32_e32 v124, v58, v128
	v_add_f32_e32 v124, v59, v124
	v_add_f32_e32 v124, v60, v124
	v_add_f32_e32 v124, v61, v124
	v_cvt_pk_bf16_f32 v142, v56, v57
	v_cvt_pk_bf16_f32 v143, v58, v59
	ds_read_b64_tr_b16 v[56:57], v195 offset:27648
	ds_read_b64_tr_b16 v[58:59], v195 offset:28160
	v_mfma_f32_32x32x16_bf16 v[100:115], v[120:123], v[136:139], v[100:115]
	v_add_f32_e32 v120, v62, v124
	v_add_f32_e32 v120, v63, v120
	v_add_f32_e32 v120, v64, v120
	v_add_f32_e32 v120, v65, v120
	v_cvt_pk_bf16_f32 v132, v60, v61
	v_cvt_pk_bf16_f32 v133, v62, v63
	ds_read_b64_tr_b16 v[60:61], v195 offset:31744
	ds_read_b64_tr_b16 v[62:63], v195 offset:32256
	v_mfma_f32_32x32x16_bf16 v[84:99], v[116:119], v[136:139], v[84:99]
	v_add_f32_e32 v116, v66, v120
	v_add_f32_e32 v195, v67, v116
	v_cvt_pk_bf16_f32 v134, v64, v65
	v_cvt_pk_bf16_f32 v135, v66, v67
	s_add_i32 m0, s25, s59
	s_nop 0
	global_load_lds_dwordx4 v210, s[98:99]
	s_add_i32 m0, s44, s58
	s_nop 0
	global_load_lds_dwordx4 v212, s[100:101]
	s_waitcnt lgkmcnt(14)
	v_mfma_f32_32x32x16_bf16 v[4:19], v[152:155], v[196:199], v[4:19]
	v_exp_f32_e32 v100, v100
	v_exp_f32_e32 v101, v101
	v_exp_f32_e32 v102, v102
	v_exp_f32_e32 v103, v103
	s_waitcnt lgkmcnt(12)
	v_mfma_f32_32x32x16_bf16 v[20:35], v[152:155], v[68:71], v[20:35]
	v_exp_f32_e32 v104, v104
	v_exp_f32_e32 v105, v105
	v_exp_f32_e32 v106, v106
	v_exp_f32_e32 v107, v107
	v_add_u32_e32 v68, s44, v191
	ds_read_b128 v[64:67], v68
	ds_read_b128 v[120:123], v68 offset:512
	s_waitcnt lgkmcnt(12)
	v_mfma_f32_32x32x16_bf16 v[4:19], v[148:151], v[72:75], v[4:19]
	v_exp_f32_e32 v108, v108
	v_exp_f32_e32 v109, v109
	v_exp_f32_e32 v110, v110
	v_exp_f32_e32 v111, v111
	ds_read_b128 v[124:127], v68 offset:2048
	ds_read_b128 v[128:131], v68 offset:2560
	s_waitcnt lgkmcnt(12)
	v_mfma_f32_32x32x16_bf16 v[20:35], v[148:151], v[76:79], v[20:35]
	v_exp_f32_e32 v112, v112
	v_exp_f32_e32 v113, v113
	v_exp_f32_e32 v114, v114
	v_exp_f32_e32 v115, v115
	ds_read_b128 v[164:167], v68 offset:4096
	ds_read_b128 v[168:171], v68 offset:4608
	s_waitcnt lgkmcnt(12)
	v_mfma_f32_32x32x16_bf16 v[4:19], v[140:143], v[80:83], v[4:19]
	v_exp_f32_e32 v84, v84
	v_exp_f32_e32 v85, v85
	v_exp_f32_e32 v86, v86
	v_exp_f32_e32 v87, v87
	ds_read_b128 v[172:175], v68 offset:6144
	ds_read_b128 v[116:119], v68 offset:6656
	s_waitcnt lgkmcnt(12)
	v_mfma_f32_32x32x16_bf16 v[20:35], v[140:143], v[52:55], v[20:35]
	v_exp_f32_e32 v88, v88
	v_exp_f32_e32 v89, v89
	v_exp_f32_e32 v90, v90
	v_exp_f32_e32 v91, v91
	s_waitcnt lgkmcnt(10)
	v_mfma_f32_32x32x16_bf16 v[4:19], v[132:135], v[56:59], v[4:19]
	v_exp_f32_e32 v92, v92
	v_exp_f32_e32 v93, v93
	v_exp_f32_e32 v94, v94
	v_exp_f32_e32 v95, v95
	s_waitcnt lgkmcnt(8)
	v_mfma_f32_32x32x16_bf16 v[20:35], v[132:135], v[60:63], v[20:35]
	v_exp_f32_e32 v96, v96
	v_exp_f32_e32 v97, v97
	v_exp_f32_e32 v98, v98
	v_exp_f32_e32 v99, v99
	s_waitcnt vmcnt(2) lgkmcnt(0)
	s_barrier
	s_add_i32 s25, s44, 0x2000
	s_cmpk_lg_i32 s44, 0x4000
	s_cselect_b32 s25, s25, 0
	v_add_u32_e32 v200, s28, v190
	ds_read_b64_tr_b16 v[196:197], v200 offset:24576
	ds_read_b64_tr_b16 v[198:199], v200 offset:25088
	v_mfma_f32_32x32x16_bf16 v[68:83], v[64:67], v[160:163], 0
	v_add_f32_e32 v52, v100, v101
	v_add_f32_e32 v52, v102, v52
	v_add_f32_e32 v52, v103, v52
	v_add_f32_e32 v52, v104, v52
	v_add_f32_e32 v52, v105, v52
	v_cvt_pk_bf16_f32 v152, v100, v101
	v_cvt_pk_bf16_f32 v153, v102, v103
	ds_read_b64_tr_b16 v[100:101], v200 offset:28672
	ds_read_b64_tr_b16 v[102:103], v200 offset:29184
	v_add_f32_e32 v52, v106, v52
	v_add_f32_e32 v52, v107, v52
	v_add_f32_e32 v52, v108, v52
	v_add_f32_e32 v132, v109, v52
	v_mfma_f32_32x32x16_bf16 v[52:67], v[120:123], v[160:163], 0
	v_cvt_pk_bf16_f32 v154, v104, v105
	v_cvt_pk_bf16_f32 v155, v106, v107
	ds_read_b64_tr_b16 v[104:105], v200 offset:25600
	ds_read_b64_tr_b16 v[106:107], v200 offset:26112
	v_mfma_f32_32x32x16_bf16 v[68:83], v[124:127], v[156:159], v[68:83]
	v_add_f32_e32 v120, v110, v132
	v_add_f32_e32 v120, v111, v120
	v_add_f32_e32 v120, v112, v120
	v_add_f32_e32 v120, v113, v120
	v_cvt_pk_bf16_f32 v148, v108, v109
	v_cvt_pk_bf16_f32 v149, v110, v111
	ds_read_b64_tr_b16 v[108:109], v200 offset:29696
	ds_read_b64_tr_b16 v[110:111], v200 offset:30208
	v_mfma_f32_32x32x16_bf16 v[52:67], v[128:131], v[156:159], v[52:67]
	v_add_f32_e32 v120, v114, v120
	v_add_f32_e32 v120, v115, v120
	v_add_f32_e32 v120, v84, v120
	v_add_f32_e32 v120, v85, v120
	v_cvt_pk_bf16_f32 v150, v112, v113
	v_cvt_pk_bf16_f32 v151, v114, v115
	ds_read_b64_tr_b16 v[112:113], v200 offset:26624
	ds_read_b64_tr_b16 v[114:115], v200 offset:27136
	v_mfma_f32_32x32x16_bf16 v[68:83], v[164:167], v[144:147], v[68:83]
	v_add_f32_e32 v120, v86, v120
	v_add_f32_e32 v120, v87, v120
	v_add_f32_e32 v120, v88, v120
	v_add_f32_e32 v120, v89, v120
	v_cvt_pk_bf16_f32 v140, v84, v85
	v_cvt_pk_bf16_f32 v141, v86, v87
	ds_read_b64_tr_b16 v[206:207], v200 offset:30720
	ds_read_b64_tr_b16 v[208:209], v200 offset:31232
	v_mfma_f32_32x32x16_bf16 v[52:67], v[168:171], v[144:147], v[52:67]
	v_add_f32_e32 v84, v90, v120
	v_add_f32_e32 v84, v91, v84
	v_add_f32_e32 v84, v92, v84
	v_add_f32_e32 v84, v93, v84
	v_cvt_pk_bf16_f32 v142, v88, v89
	v_cvt_pk_bf16_f32 v143, v90, v91
	ds_read_b64_tr_b16 v[88:89], v200 offset:27648
	ds_read_b64_tr_b16 v[90:91], v200 offset:28160
	v_mfma_f32_32x32x16_bf16 v[68:83], v[172:175], v[136:139], v[68:83]
	v_add_f32_e32 v84, v94, v84
	v_add_f32_e32 v84, v95, v84
	v_add_f32_e32 v84, v96, v84
	v_add_f32_e32 v84, v97, v84
	v_cvt_pk_bf16_f32 v132, v92, v93
	v_cvt_pk_bf16_f32 v133, v94, v95
	ds_read_b64_tr_b16 v[92:93], v200 offset:31744
	ds_read_b64_tr_b16 v[94:95], v200 offset:32256
	v_mfma_f32_32x32x16_bf16 v[52:67], v[116:119], v[136:139], v[52:67]
	v_add_f32_e32 v84, v98, v84
	v_add_f32_e32 v200, v99, v84
	v_cvt_pk_bf16_f32 v134, v96, v97
	v_cvt_pk_bf16_f32 v135, v98, v99
	s_add_i32 m0, s44, s59
	s_nop 0
	global_load_lds_dwordx4 v214, s[98:99]
	s_add_i32 m0, s25, s58
	s_nop 0
	global_load_lds_dwordx4 v215, s[100:101]
	s_add_u32 s98, s98, s36
	s_addc_u32 s99, s99, s37
	s_add_u32 s100, s100, s36
	s_addc_u32 s101, s101, s37
	s_waitcnt lgkmcnt(14)
	v_mfma_f32_32x32x16_bf16 v[4:19], v[152:155], v[196:199], v[4:19]
	v_exp_f32_e32 v68, v68
	v_exp_f32_e32 v69, v69
	v_exp_f32_e32 v70, v70
	v_exp_f32_e32 v71, v71
	s_waitcnt lgkmcnt(12)
	v_mfma_f32_32x32x16_bf16 v[20:35], v[152:155], v[100:103], v[20:35]
	v_exp_f32_e32 v72, v72
	v_exp_f32_e32 v73, v73
	v_exp_f32_e32 v74, v74
	v_exp_f32_e32 v75, v75
	v_add_u32_e32 v96, s25, v191
	ds_read_b128 v[84:87], v96
	ds_read_b128 v[168:171], v96 offset:512
	s_waitcnt lgkmcnt(12)
	v_mfma_f32_32x32x16_bf16 v[4:19], v[148:151], v[104:107], v[4:19]
	v_exp_f32_e32 v76, v76
	v_exp_f32_e32 v77, v77
	v_exp_f32_e32 v78, v78
	v_exp_f32_e32 v79, v79
	ds_read_b128 v[172:175], v96 offset:2048
	ds_read_b128 v[164:167], v96 offset:2560
	s_waitcnt lgkmcnt(12)
	v_mfma_f32_32x32x16_bf16 v[20:35], v[148:151], v[108:111], v[20:35]
	v_exp_f32_e32 v80, v80
	v_exp_f32_e32 v81, v81
	v_exp_f32_e32 v82, v82
	v_exp_f32_e32 v83, v83
	ds_read_b128 v[128:131], v96 offset:4096
	ds_read_b128 v[124:127], v96 offset:4608
	s_waitcnt lgkmcnt(12)
	v_mfma_f32_32x32x16_bf16 v[4:19], v[140:143], v[112:115], v[4:19]
	v_exp_f32_e32 v52, v52
	v_exp_f32_e32 v53, v53
	v_exp_f32_e32 v54, v54
	v_exp_f32_e32 v55, v55
	ds_read_b128 v[120:123], v96 offset:6144
	ds_read_b128 v[116:119], v96 offset:6656
	s_waitcnt lgkmcnt(12)
	v_mfma_f32_32x32x16_bf16 v[20:35], v[140:143], v[206:209], v[20:35]
	v_exp_f32_e32 v56, v56
	v_exp_f32_e32 v57, v57
	v_exp_f32_e32 v58, v58
	v_exp_f32_e32 v59, v59
	s_waitcnt lgkmcnt(10)
	v_mfma_f32_32x32x16_bf16 v[4:19], v[132:135], v[88:91], v[4:19]
	v_exp_f32_e32 v60, v60
	v_exp_f32_e32 v61, v61
	v_exp_f32_e32 v62, v62
	v_exp_f32_e32 v63, v63
	s_waitcnt lgkmcnt(8)
	v_mfma_f32_32x32x16_bf16 v[20:35], v[132:135], v[92:95], v[20:35]
	v_exp_f32_e32 v64, v64
	v_exp_f32_e32 v65, v65
	v_exp_f32_e32 v66, v66
	v_exp_f32_e32 v67, v67
	s_add_i32 s28, s25, 0x2000
	s_waitcnt vmcnt(2) lgkmcnt(0)
	s_barrier
	s_cmpk_lg_i32 s25, 0x4000
	v_add_f32_e32 v88, v192, v195
	s_cselect_b32 s29, s28, 0
	s_add_i32 s24, s24, 2
	v_add_f32_e32 v192, v88, v200
	s_cmpk_gt_u32 s24, 0xf8
	s_mov_b32 s45, s44
	s_cbranch_scc0 .LBB0_731
	s_sub_u32 s98, s98, s76
	s_subb_u32 s99, s99, s77
	s_sub_u32 s100, s100, s34
	s_subb_u32 s101, s101, s35
	v_lshl_add_u64 v[0:1], s[98:99], 0, v[210:211]
	v_lshl_add_u64 v[184:185], s[100:101], 0, v[212:213]
	s_and_b32 s24, s60, 0x3fffffc0
	s_cmp_lg_u32 0, -1
	s_cselect_b32 s28, 0, 0
	s_addk_i32 s28, 0x6000
	s_lshl_b32 s24, s24, 2
	v_add3_u32 v0, v194, s28, v193
	s_add_i32 s28, s24, 0
	v_add_u32_e32 v1, s44, v190
	ds_read_b64_tr_b16 v[194:195], v1 offset:24576
	ds_read_b64_tr_b16 v[196:197], v1 offset:25088
	v_add_f32_e32 v88, v68, v69
	v_add_f32_e32 v88, v70, v88
	v_add_f32_e32 v88, v71, v88
	v_add_f32_e32 v88, v72, v88
	v_add_f32_e32 v88, v73, v88
	v_cvt_pk_bf16_f32 v152, v68, v69
	v_cvt_pk_bf16_f32 v153, v70, v71
	s_waitcnt lgkmcnt(9)
	v_mfma_f32_32x32x16_bf16 v[100:115], v[84:87], v[160:163], v[36:51]
	ds_read_b64_tr_b16 v[68:69], v1 offset:28672
	ds_read_b64_tr_b16 v[70:71], v1 offset:29184
	v_add_f32_e32 v84, v74, v88
	v_add_f32_e32 v84, v75, v84
	v_add_f32_e32 v84, v76, v84
	v_add_f32_e32 v132, v77, v84
	v_cvt_pk_bf16_f32 v154, v72, v73
	v_cvt_pk_bf16_f32 v155, v74, v75
	s_waitcnt lgkmcnt(10)
	v_mfma_f32_32x32x16_bf16 v[84:99], v[168:171], v[160:163], v[36:51]
	ds_read_b64_tr_b16 v[72:73], v1 offset:25600
	ds_read_b64_tr_b16 v[74:75], v1 offset:26112
	v_add_f32_e32 v132, v78, v132
	v_add_f32_e32 v132, v79, v132
	v_add_f32_e32 v132, v80, v132
	v_add_f32_e32 v132, v81, v132
	v_cvt_pk_bf16_f32 v148, v76, v77
	v_cvt_pk_bf16_f32 v149, v78, v79
	s_waitcnt lgkmcnt(11)
	v_mfma_f32_32x32x16_bf16 v[100:115], v[172:175], v[156:159], v[100:115]
	ds_read_b64_tr_b16 v[76:77], v1 offset:29696
	ds_read_b64_tr_b16 v[78:79], v1 offset:30208
	v_add_f32_e32 v132, v82, v132
	v_add_f32_e32 v132, v83, v132
	v_add_f32_e32 v132, v52, v132
	v_add_f32_e32 v132, v53, v132
	v_cvt_pk_bf16_f32 v150, v80, v81
	v_cvt_pk_bf16_f32 v151, v82, v83
	s_waitcnt lgkmcnt(12)
	v_mfma_f32_32x32x16_bf16 v[84:99], v[164:167], v[156:159], v[84:99]
	ds_read_b64_tr_b16 v[80:81], v1 offset:26624
	ds_read_b64_tr_b16 v[82:83], v1 offset:27136
	s_waitcnt lgkmcnt(13)
	v_mfma_f32_32x32x16_bf16 v[100:115], v[128:131], v[144:147], v[100:115]
	v_add_f32_e32 v128, v54, v132
	v_add_f32_e32 v128, v55, v128
	v_add_f32_e32 v128, v56, v128
	v_add_f32_e32 v128, v57, v128
	v_cvt_pk_bf16_f32 v140, v52, v53
	v_cvt_pk_bf16_f32 v141, v54, v55
	ds_read_b64_tr_b16 v[52:53], v1 offset:30720
	ds_read_b64_tr_b16 v[54:55], v1 offset:31232
	s_waitcnt lgkmcnt(14)
	v_mfma_f32_32x32x16_bf16 v[84:99], v[124:127], v[144:147], v[84:99]
	v_add_f32_e32 v124, v58, v128
	v_add_f32_e32 v124, v59, v124
	v_add_f32_e32 v124, v60, v124
	v_add_f32_e32 v124, v61, v124
	v_cvt_pk_bf16_f32 v142, v56, v57
	v_cvt_pk_bf16_f32 v143, v58, v59
	ds_read_b64_tr_b16 v[56:57], v1 offset:27648
	ds_read_b64_tr_b16 v[58:59], v1 offset:28160
	s_waitcnt lgkmcnt(14)
	v_mfma_f32_32x32x16_bf16 v[100:115], v[120:123], v[136:139], v[100:115]
	v_add_f32_e32 v120, v62, v124
	v_add_f32_e32 v120, v63, v120
	v_add_f32_e32 v120, v64, v120
	v_add_f32_e32 v120, v65, v120
	v_cvt_pk_bf16_f32 v132, v60, v61
	v_cvt_pk_bf16_f32 v133, v62, v63
	ds_read_b64_tr_b16 v[60:61], v1 offset:31744
	ds_read_b64_tr_b16 v[62:63], v1 offset:32256
	v_add_f32_e32 v1, v66, v120
	v_add_f32_e32 v1, v67, v1
	v_add_f32_e32 v1, 0, v1
	v_cvt_pk_bf16_f32 v134, v64, v65
	v_cvt_pk_bf16_f32 v135, v66, v67
	v_mfma_f32_32x32x16_bf16 v[84:99], v[116:119], v[136:139], v[84:99]
	s_mov_b64 s[46:47], 0x3f8000
	s_add_i32 s24, s25, s59
	v_lshl_add_u64 v[64:65], v[182:183], 0, s[46:47]
	s_mov_b32 s44, m0
	s_mov_b32 m0, s24
	s_nop 0
	global_load_lds_dwordx4 v[64:65], off
	s_mov_b32 m0, s44
	s_mov_b64 s[44:45], 0x3f0000
	v_lshl_add_u64 v[64:65], v[180:181], 0, s[44:45]
	s_add_i32 s24, s29, s58
	s_mov_b32 s44, m0
	s_mov_b32 m0, s24
	s_nop 0
	global_load_lds_dwordx4 v[64:65], off
	s_mov_b32 m0, s44
	v_add_f32_e32 v1, v192, v1
	s_waitcnt lgkmcnt(14)
	v_mfma_f32_32x32x16_bf16 v[4:19], v[152:155], v[194:197], v[4:19]
	v_exp_f32_e32 v100, v100
	v_exp_f32_e32 v101, v101
	v_exp_f32_e32 v102, v102
	v_exp_f32_e32 v103, v103
	s_waitcnt lgkmcnt(12)
	v_mfma_f32_32x32x16_bf16 v[20:35], v[152:155], v[68:71], v[20:35]
	v_exp_f32_e32 v104, v104
	v_exp_f32_e32 v105, v105
	v_exp_f32_e32 v106, v106
	v_exp_f32_e32 v107, v107
	v_add_u32_e32 v68, s29, v191
	ds_read_b128 v[64:67], v68
	ds_read_b128 v[164:167], v68 offset:512
	s_waitcnt lgkmcnt(12)
	v_mfma_f32_32x32x16_bf16 v[4:19], v[148:151], v[72:75], v[4:19]
	v_exp_f32_e32 v108, v108
	v_exp_f32_e32 v109, v109
	v_exp_f32_e32 v110, v110
	v_exp_f32_e32 v111, v111
	ds_read_b128 v[72:75], v68 offset:2048
	ds_read_b128 v[168:171], v68 offset:2560
	s_waitcnt lgkmcnt(12)
	v_mfma_f32_32x32x16_bf16 v[20:35], v[148:151], v[76:79], v[20:35]
	v_exp_f32_e32 v112, v112
	v_exp_f32_e32 v113, v113
	v_exp_f32_e32 v114, v114
	v_exp_f32_e32 v115, v115
	ds_read_b128 v[76:79], v68 offset:4096
	ds_read_b128 v[172:175], v68 offset:4608
	s_waitcnt lgkmcnt(12)
	v_mfma_f32_32x32x16_bf16 v[4:19], v[140:143], v[80:83], v[4:19]
	v_exp_f32_e32 v84, v84
	v_exp_f32_e32 v85, v85
	v_exp_f32_e32 v86, v86
	v_exp_f32_e32 v87, v87
	ds_read_b128 v[80:83], v68 offset:6144
	ds_read_b128 v[68:71], v68 offset:6656
	s_waitcnt lgkmcnt(12)
	v_mfma_f32_32x32x16_bf16 v[20:35], v[140:143], v[52:55], v[20:35]
	v_exp_f32_e32 v88, v88
	v_exp_f32_e32 v89, v89
	v_exp_f32_e32 v90, v90
	v_exp_f32_e32 v91, v91
	s_waitcnt lgkmcnt(10)
	v_mfma_f32_32x32x16_bf16 v[4:19], v[132:135], v[56:59], v[4:19]
	v_exp_f32_e32 v92, v92
	v_exp_f32_e32 v93, v93
	v_exp_f32_e32 v94, v94
	v_exp_f32_e32 v95, v95
	s_waitcnt lgkmcnt(8)
	v_mfma_f32_32x32x16_bf16 v[20:35], v[132:135], v[60:63], v[20:35]
	v_exp_f32_e32 v96, v96
	v_exp_f32_e32 v97, v97
	v_exp_f32_e32 v98, v98
	v_exp_f32_e32 v99, v99
	s_waitcnt vmcnt(2) lgkmcnt(0)
	s_barrier
	s_add_i32 s24, s29, 0x2000
	s_cmpk_lg_i32 s29, 0x4000
	s_cselect_b32 s44, s24, 0
	v_add_u32_e32 v184, s25, v190
	ds_read_b64_tr_b16 v[192:193], v184 offset:24576
	ds_read_b64_tr_b16 v[194:195], v184 offset:25088
	v_add_f32_e32 v52, v100, v101
	v_add_f32_e32 v52, v102, v52
	v_add_f32_e32 v52, v103, v52
	v_add_f32_e32 v52, v104, v52
	v_add_f32_e32 v52, v105, v52
	v_cvt_pk_bf16_f32 v152, v100, v101
	v_cvt_pk_bf16_f32 v153, v102, v103
	s_waitcnt lgkmcnt(9)
	v_mfma_f32_32x32x16_bf16 v[116:131], v[64:67], v[160:163], v[36:51]
	ds_read_b64_tr_b16 v[100:101], v184 offset:28672
	ds_read_b64_tr_b16 v[102:103], v184 offset:29184
	v_add_f32_e32 v52, v106, v52
	v_add_f32_e32 v52, v107, v52
	v_add_f32_e32 v52, v108, v52
	v_add_f32_e32 v132, v109, v52
	v_cvt_pk_bf16_f32 v154, v104, v105
	v_cvt_pk_bf16_f32 v155, v106, v107
	s_waitcnt lgkmcnt(10)
	v_mfma_f32_32x32x16_bf16 v[52:67], v[164:167], v[160:163], v[36:51]
	ds_read_b64_tr_b16 v[104:105], v184 offset:25600
	ds_read_b64_tr_b16 v[106:107], v184 offset:26112
	s_waitcnt lgkmcnt(11)
	v_mfma_f32_32x32x16_bf16 v[116:131], v[72:75], v[156:159], v[116:131]
	v_add_f32_e32 v72, v110, v132
	v_add_f32_e32 v72, v111, v72
	v_add_f32_e32 v72, v112, v72
	v_add_f32_e32 v132, v113, v72
	v_cvt_pk_bf16_f32 v148, v108, v109
	v_cvt_pk_bf16_f32 v149, v110, v111
	ds_read_b64_tr_b16 v[72:73], v184 offset:29696
	ds_read_b64_tr_b16 v[74:75], v184 offset:30208
	v_add_f32_e32 v108, v114, v132
	v_add_f32_e32 v108, v115, v108
	v_add_f32_e32 v108, v84, v108
	v_add_f32_e32 v132, v85, v108
	v_cvt_pk_bf16_f32 v150, v112, v113
	v_cvt_pk_bf16_f32 v151, v114, v115
	s_waitcnt lgkmcnt(12)
	v_mfma_f32_32x32x16_bf16 v[52:67], v[168:171], v[156:159], v[52:67]
	ds_read_b64_tr_b16 v[108:109], v184 offset:26624
	ds_read_b64_tr_b16 v[110:111], v184 offset:27136
	s_waitcnt lgkmcnt(13)
	v_mfma_f32_32x32x16_bf16 v[116:131], v[76:79], v[144:147], v[116:131]
	v_add_f32_e32 v76, v86, v132
	v_add_f32_e32 v76, v87, v76
	v_add_f32_e32 v76, v88, v76
	v_add_f32_e32 v112, v89, v76
	v_cvt_pk_bf16_f32 v140, v84, v85
	v_cvt_pk_bf16_f32 v141, v86, v87
	ds_read_b64_tr_b16 v[76:77], v184 offset:30720
	ds_read_b64_tr_b16 v[78:79], v184 offset:31232
	v_add_f32_e32 v84, v90, v112
	v_add_f32_e32 v84, v91, v84
	v_add_f32_e32 v84, v92, v84
	v_add_f32_e32 v84, v93, v84
	v_cvt_pk_bf16_f32 v142, v88, v89
	v_cvt_pk_bf16_f32 v143, v90, v91
	s_waitcnt lgkmcnt(14)
	v_mfma_f32_32x32x16_bf16 v[52:67], v[172:175], v[144:147], v[52:67]
	ds_read_b64_tr_b16 v[88:89], v184 offset:27648
	ds_read_b64_tr_b16 v[90:91], v184 offset:28160
	s_waitcnt lgkmcnt(14)
	v_mfma_f32_32x32x16_bf16 v[116:131], v[80:83], v[136:139], v[116:131]
	v_add_f32_e32 v80, v94, v84
	v_add_f32_e32 v80, v95, v80
	v_add_f32_e32 v80, v96, v80
	v_add_f32_e32 v84, v97, v80
	v_cvt_pk_bf16_f32 v132, v92, v93
	v_cvt_pk_bf16_f32 v133, v94, v95
	ds_read_b64_tr_b16 v[80:81], v184 offset:31744
	ds_read_b64_tr_b16 v[82:83], v184 offset:32256
	v_mfma_f32_32x32x16_bf16 v[52:67], v[68:71], v[136:139], v[52:67]
	v_add_f32_e32 v68, v98, v84
	v_add_f32_e32 v68, v99, v68
	v_add_f32_e32 v68, 0, v68
	v_cvt_pk_bf16_f32 v134, v96, v97
	v_cvt_pk_bf16_f32 v135, v98, v99
	s_mov_b64 s[60:61], 0x3fc000
	v_add_f32_e32 v1, v1, v68
	s_add_i32 s24, s29, s59
	v_lshl_add_u64 v[68:69], v[182:183], 0, s[60:61]
	s_mov_b32 s25, m0
	s_mov_b32 m0, s24
	s_nop 0
	global_load_lds_dwordx4 v[68:69], off
	s_mov_b32 m0, s25
	s_mov_b64 s[24:25], 0x3f4000
	s_add_i32 s45, s44, s58
	v_lshl_add_u64 v[68:69], v[180:181], 0, s[24:25]
	s_mov_b32 s24, m0
	s_mov_b32 m0, s45
	s_nop 0
	global_load_lds_dwordx4 v[68:69], off
	s_mov_b32 m0, s24
	s_waitcnt lgkmcnt(14)
	v_mfma_f32_32x32x16_bf16 v[4:19], v[152:155], v[192:195], v[4:19]
	v_exp_f32_e32 v116, v116
	v_exp_f32_e32 v117, v117
	v_exp_f32_e32 v118, v118
	v_exp_f32_e32 v119, v119
	s_waitcnt lgkmcnt(12)
	v_mfma_f32_32x32x16_bf16 v[20:35], v[152:155], v[100:103], v[20:35]
	v_exp_f32_e32 v120, v120
	v_exp_f32_e32 v121, v121
	v_exp_f32_e32 v122, v122
	v_exp_f32_e32 v123, v123
	v_add_u32_e32 v84, s44, v191
	ds_read_b128 v[68:71], v84
	ds_read_b128 v[92:95], v84 offset:512
	s_waitcnt lgkmcnt(12)
	v_mfma_f32_32x32x16_bf16 v[4:19], v[148:151], v[104:107], v[4:19]
	v_exp_f32_e32 v124, v124
	v_exp_f32_e32 v125, v125
	v_exp_f32_e32 v126, v126
	v_exp_f32_e32 v127, v127
	ds_read_b128 v[96:99], v84 offset:2048
	ds_read_b128 v[164:167], v84 offset:2560
	s_waitcnt lgkmcnt(12)
	v_mfma_f32_32x32x16_bf16 v[20:35], v[148:151], v[72:75], v[20:35]
	v_exp_f32_e32 v128, v128
	v_exp_f32_e32 v129, v129
	v_exp_f32_e32 v130, v130
	v_exp_f32_e32 v131, v131
	ds_read_b128 v[168:171], v84 offset:4096
	ds_read_b128 v[172:175], v84 offset:4608
	s_waitcnt lgkmcnt(12)
	v_mfma_f32_32x32x16_bf16 v[4:19], v[140:143], v[108:111], v[4:19]
	v_exp_f32_e32 v52, v52
	v_exp_f32_e32 v53, v53
	v_exp_f32_e32 v54, v54
	v_exp_f32_e32 v55, v55
	ds_read_b128 v[182:185], v84 offset:6144
	ds_read_b128 v[84:87], v84 offset:6656
	s_waitcnt lgkmcnt(12)
	v_mfma_f32_32x32x16_bf16 v[20:35], v[140:143], v[76:79], v[20:35]
	v_exp_f32_e32 v56, v56
	v_exp_f32_e32 v57, v57
	v_exp_f32_e32 v58, v58
	v_exp_f32_e32 v59, v59
	s_waitcnt lgkmcnt(10)
	v_mfma_f32_32x32x16_bf16 v[4:19], v[132:135], v[88:91], v[4:19]
	v_exp_f32_e32 v60, v60
	v_exp_f32_e32 v61, v61
	v_exp_f32_e32 v62, v62
	v_exp_f32_e32 v63, v63
	s_waitcnt lgkmcnt(8)
	v_mfma_f32_32x32x16_bf16 v[20:35], v[132:135], v[80:83], v[20:35]
	v_exp_f32_e32 v64, v64
	v_exp_f32_e32 v65, v65
	v_exp_f32_e32 v66, v66
	v_exp_f32_e32 v67, v67
	s_waitcnt vmcnt(2) lgkmcnt(0)
	s_barrier
	s_add_i32 s24, s44, 0x2000
	s_cmpk_lg_i32 s44, 0x4000
	s_cselect_b32 s25, s24, 0
	v_add_u32_e32 v192, s29, v190
	ds_read_b64_tr_b16 v[88:89], v192 offset:24576
	ds_read_b64_tr_b16 v[90:91], v192 offset:25088
	v_add_f32_e32 v72, v116, v117
	v_add_f32_e32 v72, v118, v72
	v_add_f32_e32 v72, v119, v72
	v_add_f32_e32 v72, v120, v72
	v_add_f32_e32 v72, v121, v72
	v_cvt_pk_bf16_f32 v152, v116, v117
	v_cvt_pk_bf16_f32 v153, v118, v119
	s_waitcnt lgkmcnt(9)
	v_mfma_f32_32x32x16_bf16 v[100:115], v[68:71], v[160:163], v[36:51]
	ds_read_b64_tr_b16 v[116:117], v192 offset:28672
	ds_read_b64_tr_b16 v[118:119], v192 offset:29184
	v_add_f32_e32 v68, v122, v72
	v_add_f32_e32 v68, v123, v68
	v_add_f32_e32 v68, v124, v68
	v_add_f32_e32 v132, v125, v68
	v_cvt_pk_bf16_f32 v154, v120, v121
	v_cvt_pk_bf16_f32 v155, v122, v123
	s_waitcnt lgkmcnt(10)
	v_mfma_f32_32x32x16_bf16 v[68:83], v[92:95], v[160:163], v[36:51]
	ds_read_b64_tr_b16 v[92:93], v192 offset:25600
	ds_read_b64_tr_b16 v[94:95], v192 offset:26112
	s_waitcnt lgkmcnt(11)
	v_mfma_f32_32x32x16_bf16 v[100:115], v[96:99], v[156:159], v[100:115]
	v_add_f32_e32 v96, v126, v132
	v_add_f32_e32 v96, v127, v96
	v_add_f32_e32 v96, v128, v96
	v_add_f32_e32 v120, v129, v96
	v_cvt_pk_bf16_f32 v148, v124, v125
	v_cvt_pk_bf16_f32 v149, v126, v127
	ds_read_b64_tr_b16 v[96:97], v192 offset:29696
	ds_read_b64_tr_b16 v[98:99], v192 offset:30208
	v_add_f32_e32 v120, v130, v120
	v_add_f32_e32 v120, v131, v120
	v_add_f32_e32 v120, v52, v120
	v_add_f32_e32 v124, v53, v120
	v_cvt_pk_bf16_f32 v150, v128, v129
	v_cvt_pk_bf16_f32 v151, v130, v131
	s_waitcnt lgkmcnt(12)
	v_mfma_f32_32x32x16_bf16 v[68:83], v[164:167], v[156:159], v[68:83]
	ds_read_b64_tr_b16 v[120:121], v192 offset:26624
	ds_read_b64_tr_b16 v[122:123], v192 offset:27136
	v_add_f32_e32 v124, v54, v124
	v_add_f32_e32 v124, v55, v124
	v_add_f32_e32 v124, v56, v124
	v_add_f32_e32 v124, v57, v124
	v_cvt_pk_bf16_f32 v140, v52, v53
	v_cvt_pk_bf16_f32 v141, v54, v55
	s_waitcnt lgkmcnt(13)
	v_mfma_f32_32x32x16_bf16 v[100:115], v[168:171], v[144:147], v[100:115]
	ds_read_b64_tr_b16 v[52:53], v192 offset:30720
	ds_read_b64_tr_b16 v[54:55], v192 offset:31232
	v_add_f32_e32 v124, v58, v124
	v_add_f32_e32 v124, v59, v124
	v_add_f32_e32 v124, v60, v124
	v_add_f32_e32 v124, v61, v124
	v_cvt_pk_bf16_f32 v142, v56, v57
	v_cvt_pk_bf16_f32 v143, v58, v59
	s_waitcnt lgkmcnt(14)
	v_mfma_f32_32x32x16_bf16 v[68:83], v[172:175], v[144:147], v[68:83]
	ds_read_b64_tr_b16 v[56:57], v192 offset:27648
	ds_read_b64_tr_b16 v[58:59], v192 offset:28160
	v_add_f32_e32 v124, v62, v124
	v_add_f32_e32 v124, v63, v124
	v_add_f32_e32 v124, v64, v124
	v_add_f32_e32 v124, v65, v124
	v_cvt_pk_bf16_f32 v132, v60, v61
	v_cvt_pk_bf16_f32 v133, v62, v63
	s_waitcnt lgkmcnt(14)
	v_mfma_f32_32x32x16_bf16 v[100:115], v[182:185], v[136:139], v[100:115]
	ds_read_b64_tr_b16 v[60:61], v192 offset:31744
	ds_read_b64_tr_b16 v[62:63], v192 offset:32256
	v_mfma_f32_32x32x16_bf16 v[68:83], v[84:87], v[136:139], v[68:83]
	v_add_f32_e32 v84, v66, v124
	v_add_f32_e32 v84, v67, v84
	v_add_f32_e32 v84, 0, v84
	v_cvt_pk_bf16_f32 v134, v64, v65
	v_cvt_pk_bf16_f32 v135, v66, v67
	v_lshl_add_u64 v[64:65], v[180:181], 0, s[46:47]
	s_add_i32 s24, s25, s58
	s_mov_b32 s29, m0
	s_mov_b32 m0, s24
	s_nop 0
	global_load_lds_dwordx4 v[64:65], off
	s_mov_b32 m0, s29
	v_add_f32_e32 v1, v1, v84
	s_waitcnt lgkmcnt(14)
	v_mfma_f32_32x32x16_bf16 v[4:19], v[152:155], v[88:91], v[4:19]
	v_exp_f32_e32 v100, v100
	v_exp_f32_e32 v101, v101
	v_exp_f32_e32 v102, v102
	v_exp_f32_e32 v103, v103
	s_waitcnt lgkmcnt(12)
	v_mfma_f32_32x32x16_bf16 v[20:35], v[152:155], v[116:119], v[20:35]
	v_exp_f32_e32 v104, v104
	v_exp_f32_e32 v105, v105
	v_exp_f32_e32 v106, v106
	v_exp_f32_e32 v107, v107
	v_add_u32_e32 v84, s25, v191
	ds_read_b128 v[64:67], v84
	ds_read_b128 v[124:127], v84 offset:512
	s_waitcnt lgkmcnt(12)
	v_mfma_f32_32x32x16_bf16 v[4:19], v[148:151], v[92:95], v[4:19]
	v_exp_f32_e32 v108, v108
	v_exp_f32_e32 v109, v109
	v_exp_f32_e32 v110, v110
	v_exp_f32_e32 v111, v111
	ds_read_b128 v[128:131], v84 offset:2048
	ds_read_b128 v[164:167], v84 offset:2560
	s_waitcnt lgkmcnt(12)
	v_mfma_f32_32x32x16_bf16 v[20:35], v[148:151], v[96:99], v[20:35]
	v_exp_f32_e32 v112, v112
	v_exp_f32_e32 v113, v113
	v_exp_f32_e32 v114, v114
	v_exp_f32_e32 v115, v115
	ds_read_b128 v[168:171], v84 offset:4096
	ds_read_b128 v[172:175], v84 offset:4608
	s_waitcnt lgkmcnt(12)
	v_mfma_f32_32x32x16_bf16 v[4:19], v[140:143], v[120:123], v[4:19]
	v_exp_f32_e32 v68, v68
	v_exp_f32_e32 v69, v69
	v_exp_f32_e32 v70, v70
	v_exp_f32_e32 v71, v71
	ds_read_b128 v[120:123], v84 offset:6144
	ds_read_b128 v[116:119], v84 offset:6656
	s_waitcnt lgkmcnt(12)
	v_mfma_f32_32x32x16_bf16 v[20:35], v[140:143], v[52:55], v[20:35]
	v_exp_f32_e32 v72, v72
	v_exp_f32_e32 v73, v73
	v_exp_f32_e32 v74, v74
	v_exp_f32_e32 v75, v75
	s_waitcnt lgkmcnt(10)
	v_mfma_f32_32x32x16_bf16 v[4:19], v[132:135], v[56:59], v[4:19]
	v_exp_f32_e32 v76, v76
	v_exp_f32_e32 v77, v77
	v_exp_f32_e32 v78, v78
	v_exp_f32_e32 v79, v79
	s_waitcnt lgkmcnt(8)
	v_mfma_f32_32x32x16_bf16 v[20:35], v[132:135], v[60:63], v[20:35]
	v_exp_f32_e32 v80, v80
	v_exp_f32_e32 v81, v81
	v_exp_f32_e32 v82, v82
	v_exp_f32_e32 v83, v83
	s_waitcnt vmcnt(1) lgkmcnt(0)
	s_barrier
	s_add_i32 s24, s25, 0x2000
	s_cmpk_lg_i32 s25, 0x4000
	s_cselect_b32 s24, s24, 0
	v_add_u32_e32 v192, s44, v190
	ds_read_b64_tr_b16 v[182:183], v192 offset:24576
	ds_read_b64_tr_b16 v[184:185], v192 offset:25088
	v_add_f32_e32 v52, v100, v101
	v_add_f32_e32 v52, v102, v52
	v_add_f32_e32 v52, v103, v52
	v_add_f32_e32 v52, v104, v52
	v_add_f32_e32 v52, v105, v52
	v_cvt_pk_bf16_f32 v152, v100, v101
	v_cvt_pk_bf16_f32 v153, v102, v103
	s_waitcnt lgkmcnt(9)
	v_mfma_f32_32x32x16_bf16 v[84:99], v[64:67], v[160:163], v[36:51]
	ds_read_b64_tr_b16 v[100:101], v192 offset:28672
	ds_read_b64_tr_b16 v[102:103], v192 offset:29184
	v_add_f32_e32 v52, v106, v52
	v_add_f32_e32 v52, v107, v52
	v_add_f32_e32 v52, v108, v52
	v_add_f32_e32 v132, v109, v52
	v_cvt_pk_bf16_f32 v154, v104, v105
	v_cvt_pk_bf16_f32 v155, v106, v107
	s_waitcnt lgkmcnt(10)
	v_mfma_f32_32x32x16_bf16 v[52:67], v[124:127], v[160:163], v[36:51]
	ds_read_b64_tr_b16 v[104:105], v192 offset:25600
	ds_read_b64_tr_b16 v[106:107], v192 offset:26112
	v_add_f32_e32 v124, v110, v132
	v_add_f32_e32 v124, v111, v124
	v_add_f32_e32 v124, v112, v124
	v_add_f32_e32 v124, v113, v124
	v_cvt_pk_bf16_f32 v148, v108, v109
	v_cvt_pk_bf16_f32 v149, v110, v111
	s_waitcnt lgkmcnt(11)
	v_mfma_f32_32x32x16_bf16 v[84:99], v[128:131], v[156:159], v[84:99]
	ds_read_b64_tr_b16 v[108:109], v192 offset:29696
	ds_read_b64_tr_b16 v[110:111], v192 offset:30208
	v_add_f32_e32 v124, v114, v124
	v_add_f32_e32 v124, v115, v124
	v_add_f32_e32 v124, v68, v124
	v_add_f32_e32 v124, v69, v124
	v_cvt_pk_bf16_f32 v150, v112, v113
	v_cvt_pk_bf16_f32 v151, v114, v115
	s_waitcnt lgkmcnt(12)
	v_mfma_f32_32x32x16_bf16 v[52:67], v[164:167], v[156:159], v[52:67]
	ds_read_b64_tr_b16 v[112:113], v192 offset:26624
	ds_read_b64_tr_b16 v[114:115], v192 offset:27136
	v_add_f32_e32 v124, v70, v124
	v_add_f32_e32 v124, v71, v124
	v_add_f32_e32 v124, v72, v124
	v_add_f32_e32 v124, v73, v124
	v_cvt_pk_bf16_f32 v140, v68, v69
	v_cvt_pk_bf16_f32 v141, v70, v71
	s_waitcnt lgkmcnt(13)
	v_mfma_f32_32x32x16_bf16 v[84:99], v[168:171], v[144:147], v[84:99]
	ds_read_b64_tr_b16 v[68:69], v192 offset:30720
	ds_read_b64_tr_b16 v[70:71], v192 offset:31232
	v_add_f32_e32 v124, v74, v124
	v_add_f32_e32 v124, v75, v124
	v_add_f32_e32 v124, v76, v124
	v_add_f32_e32 v124, v77, v124
	v_cvt_pk_bf16_f32 v142, v72, v73
	v_cvt_pk_bf16_f32 v143, v74, v75
	s_waitcnt lgkmcnt(14)
	v_mfma_f32_32x32x16_bf16 v[52:67], v[172:175], v[144:147], v[52:67]
	ds_read_b64_tr_b16 v[72:73], v192 offset:27648
	ds_read_b64_tr_b16 v[74:75], v192 offset:28160
	s_waitcnt lgkmcnt(14)
	v_mfma_f32_32x32x16_bf16 v[84:99], v[120:123], v[136:139], v[84:99]
	v_add_f32_e32 v120, v78, v124
	v_add_f32_e32 v120, v79, v120
	v_add_f32_e32 v120, v80, v120
	v_add_f32_e32 v120, v81, v120
	v_cvt_pk_bf16_f32 v132, v76, v77
	v_cvt_pk_bf16_f32 v133, v78, v79
	ds_read_b64_tr_b16 v[76:77], v192 offset:31744
	ds_read_b64_tr_b16 v[78:79], v192 offset:32256
	v_mfma_f32_32x32x16_bf16 v[52:67], v[116:119], v[136:139], v[52:67]
	v_add_f32_e32 v116, v82, v120
	v_add_f32_e32 v116, v83, v116
	v_add_f32_e32 v116, 0, v116
	v_cvt_pk_bf16_f32 v134, v80, v81
	v_cvt_pk_bf16_f32 v135, v82, v83
	s_add_i32 s29, s24, s58
	v_lshl_add_u64 v[80:81], v[180:181], 0, s[60:61]
	s_mov_b32 s44, m0
	s_mov_b32 m0, s29
	s_nop 0
	global_load_lds_dwordx4 v[80:81], off
	s_mov_b32 m0, s44
	v_add_f32_e32 v1, v1, v116
	s_waitcnt lgkmcnt(14)
	v_mfma_f32_32x32x16_bf16 v[4:19], v[152:155], v[182:185], v[4:19]
	v_exp_f32_e32 v84, v84
	v_exp_f32_e32 v85, v85
	v_exp_f32_e32 v86, v86
	v_exp_f32_e32 v87, v87
	s_waitcnt lgkmcnt(12)
	v_mfma_f32_32x32x16_bf16 v[20:35], v[152:155], v[100:103], v[20:35]
	v_exp_f32_e32 v88, v88
	v_exp_f32_e32 v89, v89
	v_exp_f32_e32 v90, v90
	v_exp_f32_e32 v91, v91
	v_add_u32_e32 v80, s24, v191
	ds_read_b128 v[116:119], v80
	ds_read_b128 v[120:123], v80 offset:512
	s_waitcnt lgkmcnt(12)
	v_mfma_f32_32x32x16_bf16 v[4:19], v[148:151], v[104:107], v[4:19]
	v_exp_f32_e32 v92, v92
	v_exp_f32_e32 v93, v93
	v_exp_f32_e32 v94, v94
	v_exp_f32_e32 v95, v95
	ds_read_b128 v[104:107], v80 offset:2048
	ds_read_b128 v[124:127], v80 offset:2560
	s_waitcnt lgkmcnt(12)
	v_mfma_f32_32x32x16_bf16 v[20:35], v[148:151], v[108:111], v[20:35]
	v_exp_f32_e32 v96, v96
	v_exp_f32_e32 v97, v97
	v_exp_f32_e32 v98, v98
	v_exp_f32_e32 v99, v99
	ds_read_b128 v[108:111], v80 offset:4096
	ds_read_b128 v[128:131], v80 offset:4608
	s_waitcnt lgkmcnt(12)
	v_mfma_f32_32x32x16_bf16 v[4:19], v[140:143], v[112:115], v[4:19]
	v_exp_f32_e32 v52, v52
	v_exp_f32_e32 v53, v53
	v_exp_f32_e32 v54, v54
	v_exp_f32_e32 v55, v55
	ds_read_b128 v[112:115], v80 offset:6144
	ds_read_b128 v[100:103], v80 offset:6656
	s_waitcnt lgkmcnt(12)
	v_mfma_f32_32x32x16_bf16 v[20:35], v[140:143], v[68:71], v[20:35]
	v_exp_f32_e32 v56, v56
	v_exp_f32_e32 v57, v57
	v_exp_f32_e32 v58, v58
	v_exp_f32_e32 v59, v59
	s_waitcnt lgkmcnt(10)
	v_mfma_f32_32x32x16_bf16 v[4:19], v[132:135], v[72:75], v[4:19]
	v_exp_f32_e32 v60, v60
	v_exp_f32_e32 v61, v61
	v_exp_f32_e32 v62, v62
	v_exp_f32_e32 v63, v63
	s_waitcnt lgkmcnt(8)
	v_mfma_f32_32x32x16_bf16 v[20:35], v[132:135], v[76:79], v[20:35]
	v_exp_f32_e32 v64, v64
	v_exp_f32_e32 v65, v65
	v_exp_f32_e32 v66, v66
	v_exp_f32_e32 v67, v67
	s_waitcnt vmcnt(0) lgkmcnt(0)
	s_barrier
	v_add_u32_e32 v168, s25, v190
	ds_read_b64_tr_b16 v[164:165], v168 offset:24576
	ds_read_b64_tr_b16 v[166:167], v168 offset:25088
	v_add_f32_e32 v68, v84, v85
	v_add_f32_e32 v68, v86, v68
	v_add_f32_e32 v68, v87, v68
	v_add_f32_e32 v68, v88, v68
	v_add_f32_e32 v132, v89, v68
	v_cvt_pk_bf16_f32 v152, v84, v85
	v_cvt_pk_bf16_f32 v153, v86, v87
	s_waitcnt lgkmcnt(9)
	v_mfma_f32_32x32x16_bf16 v[68:83], v[116:119], v[160:163], v[36:51]
	ds_read_b64_tr_b16 v[84:85], v168 offset:28672
	ds_read_b64_tr_b16 v[86:87], v168 offset:29184
	v_add_f32_e32 v116, v90, v132
	v_add_f32_e32 v116, v91, v116
	v_add_f32_e32 v116, v92, v116
	v_add_f32_e32 v116, v93, v116
	v_cvt_pk_bf16_f32 v154, v88, v89
	v_cvt_pk_bf16_f32 v155, v90, v91
	s_waitcnt lgkmcnt(10)
	v_mfma_f32_32x32x16_bf16 v[36:51], v[120:123], v[160:163], v[36:51]
	ds_read_b64_tr_b16 v[88:89], v168 offset:25600
	ds_read_b64_tr_b16 v[90:91], v168 offset:26112
	s_waitcnt lgkmcnt(11)
	v_mfma_f32_32x32x16_bf16 v[68:83], v[104:107], v[156:159], v[68:83]
	v_add_f32_e32 v104, v94, v116
	v_add_f32_e32 v104, v95, v104
	v_add_f32_e32 v104, v96, v104
	v_add_f32_e32 v104, v97, v104
	v_cvt_pk_bf16_f32 v148, v92, v93
	v_cvt_pk_bf16_f32 v149, v94, v95
	ds_read_b64_tr_b16 v[92:93], v168 offset:29696
	ds_read_b64_tr_b16 v[94:95], v168 offset:30208
	v_add_f32_e32 v104, v98, v104
	v_add_f32_e32 v104, v99, v104
	v_add_f32_e32 v104, v52, v104
	v_add_f32_e32 v104, v53, v104
	v_cvt_pk_bf16_f32 v150, v96, v97
	v_cvt_pk_bf16_f32 v151, v98, v99
	s_waitcnt lgkmcnt(12)
	v_mfma_f32_32x32x16_bf16 v[36:51], v[124:127], v[156:159], v[36:51]
	ds_read_b64_tr_b16 v[96:97], v168 offset:26624
	ds_read_b64_tr_b16 v[98:99], v168 offset:27136
	v_add_f32_e32 v104, v54, v104
	v_add_f32_e32 v104, v55, v104
	v_add_f32_e32 v104, v56, v104
	v_add_f32_e32 v104, v57, v104
	v_cvt_pk_bf16_f32 v140, v52, v53
	v_cvt_pk_bf16_f32 v141, v54, v55
	s_waitcnt lgkmcnt(13)
	v_mfma_f32_32x32x16_bf16 v[68:83], v[108:111], v[144:147], v[68:83]
	ds_read_b64_tr_b16 v[52:53], v168 offset:30720
	ds_read_b64_tr_b16 v[54:55], v168 offset:31232
	v_add_f32_e32 v104, v58, v104
	v_add_f32_e32 v104, v59, v104
	v_add_f32_e32 v104, v60, v104
	v_add_f32_e32 v104, v61, v104
	v_cvt_pk_bf16_f32 v142, v56, v57
	v_cvt_pk_bf16_f32 v143, v58, v59
	s_waitcnt lgkmcnt(14)
	v_mfma_f32_32x32x16_bf16 v[36:51], v[128:131], v[144:147], v[36:51]
	ds_read_b64_tr_b16 v[56:57], v168 offset:27648
	ds_read_b64_tr_b16 v[58:59], v168 offset:28160
	v_add_f32_e32 v104, v62, v104
	v_add_f32_e32 v104, v63, v104
	v_add_f32_e32 v104, v64, v104
	v_add_f32_e32 v104, v65, v104
	v_cvt_pk_bf16_f32 v132, v60, v61
	v_cvt_pk_bf16_f32 v133, v62, v63
	s_waitcnt lgkmcnt(14)
	v_mfma_f32_32x32x16_bf16 v[68:83], v[112:115], v[136:139], v[68:83]
	ds_read_b64_tr_b16 v[60:61], v168 offset:31744
	ds_read_b64_tr_b16 v[62:63], v168 offset:32256
	v_mfma_f32_32x32x16_bf16 v[36:51], v[100:103], v[136:139], v[36:51]
	v_add_f32_e32 v100, v66, v104
	v_add_f32_e32 v100, v67, v100
	v_add_f32_e32 v100, 0, v100
	v_cvt_pk_bf16_f32 v134, v64, v65
	v_cvt_pk_bf16_f32 v135, v66, v67
	s_waitcnt lgkmcnt(14)
	v_mfma_f32_32x32x16_bf16 v[4:19], v[152:155], v[164:167], v[4:19]
	s_nop 1
	v_exp_f32_e32 v68, v68
	v_exp_f32_e32 v69, v69
	v_exp_f32_e32 v70, v70
	v_exp_f32_e32 v71, v71
	s_waitcnt lgkmcnt(12)
	v_mfma_f32_32x32x16_bf16 v[20:35], v[152:155], v[84:87], v[20:35]
	v_exp_f32_e32 v72, v72
	v_exp_f32_e32 v73, v73
	v_exp_f32_e32 v74, v74
	v_exp_f32_e32 v75, v75
	s_waitcnt lgkmcnt(10)
	v_mfma_f32_32x32x16_bf16 v[4:19], v[148:151], v[88:91], v[4:19]
	v_exp_f32_e32 v76, v76
	v_exp_f32_e32 v77, v77
	v_exp_f32_e32 v78, v78
	v_exp_f32_e32 v79, v79
	s_waitcnt lgkmcnt(8)
	v_mfma_f32_32x32x16_bf16 v[20:35], v[148:151], v[92:95], v[20:35]
	v_exp_f32_e32 v80, v80
	v_exp_f32_e32 v81, v81
	v_exp_f32_e32 v82, v82
	v_exp_f32_e32 v83, v83
	s_waitcnt lgkmcnt(6)
	v_mfma_f32_32x32x16_bf16 v[4:19], v[140:143], v[96:99], v[4:19]
	v_exp_f32_e32 v36, v36
	v_exp_f32_e32 v37, v37
	v_exp_f32_e32 v38, v38
	v_exp_f32_e32 v39, v39
	s_waitcnt lgkmcnt(4)
	v_mfma_f32_32x32x16_bf16 v[20:35], v[140:143], v[52:55], v[20:35]
	v_exp_f32_e32 v40, v40
	v_exp_f32_e32 v41, v41
	v_exp_f32_e32 v42, v42
	v_exp_f32_e32 v43, v43
	s_waitcnt lgkmcnt(2)
	v_mfma_f32_32x32x16_bf16 v[4:19], v[132:135], v[56:59], v[4:19]
	v_exp_f32_e32 v44, v44
	v_exp_f32_e32 v45, v45
	v_exp_f32_e32 v46, v46
	v_exp_f32_e32 v47, v47
	s_waitcnt lgkmcnt(0)
	v_mfma_f32_32x32x16_bf16 v[20:35], v[132:135], v[60:63], v[20:35]
	v_exp_f32_e32 v48, v48
	v_exp_f32_e32 v49, v49
	v_exp_f32_e32 v50, v50
	v_exp_f32_e32 v51, v51
	v_add_f32_e32 v52, v68, v69
	v_add_f32_e32 v52, v70, v52
	v_add_f32_e32 v52, v71, v52
	v_add_f32_e32 v52, v72, v52
	v_add_f32_e32 v52, v73, v52
	v_add_f32_e32 v52, v74, v52
	v_add_f32_e32 v52, v75, v52
	v_add_f32_e32 v52, v76, v52
	v_add_f32_e32 v52, v77, v52
	v_add_f32_e32 v52, v78, v52
	v_add_f32_e32 v52, v79, v52
	v_add_f32_e32 v52, v80, v52
	v_add_f32_e32 v52, v81, v52
	v_add_f32_e32 v52, v82, v52
	v_add_f32_e32 v52, v83, v52
	v_add_f32_e32 v52, v36, v52
	v_add_f32_e32 v52, v37, v52
	v_add_f32_e32 v52, v38, v52
	v_add_f32_e32 v52, v39, v52
	v_add_f32_e32 v52, v40, v52
	v_add_f32_e32 v52, v41, v52
	v_add_f32_e32 v52, v42, v52
	v_add_f32_e32 v52, v43, v52
	v_add_f32_e32 v52, v44, v52
	v_add_f32_e32 v52, v45, v52
	v_add_f32_e32 v52, v46, v52
	v_add_f32_e32 v52, v47, v52
	v_add_f32_e32 v52, v48, v52
	v_add_f32_e32 v52, v49, v52
	v_add_f32_e32 v52, v50, v52
	v_add_f32_e32 v52, v51, v52
	v_add_f32_e32 v1, v1, v100
	v_add_f32_e32 v1, v1, v52
	v_cvt_pk_bf16_f32 v52, v68, v69
	v_cvt_pk_bf16_f32 v53, v70, v71
	v_cvt_pk_bf16_f32 v54, v72, v73
	v_cvt_pk_bf16_f32 v55, v74, v75
	v_cvt_pk_bf16_f32 v56, v76, v77
	v_cvt_pk_bf16_f32 v57, v78, v79
	v_cvt_pk_bf16_f32 v58, v80, v81
	v_cvt_pk_bf16_f32 v59, v82, v83
	v_cvt_pk_bf16_f32 v36, v36, v37
	v_cvt_pk_bf16_f32 v37, v38, v39
	v_cvt_pk_bf16_f32 v38, v40, v41
	v_cvt_pk_bf16_f32 v39, v42, v43
	v_cvt_pk_bf16_f32 v40, v44, v45
	v_cvt_pk_bf16_f32 v41, v46, v47
	v_cvt_pk_bf16_f32 v42, v48, v49
	v_cvt_pk_bf16_f32 v43, v50, v51
	v_add3_u32 v0, v0, v3, s24
	ds_read_b64_tr_b16 v[44:45],v0 offset:0
	ds_read_b64_tr_b16 v[46:47],v0 offset:512
	ds_read_b64_tr_b16 v[48:49],v0 offset:1024
	ds_read_b64_tr_b16 v[50:51],v0 offset:1536
	ds_read_b64_tr_b16 v[60:61],v0 offset:2048
	ds_read_b64_tr_b16 v[62:63],v0 offset:2560
	ds_read_b64_tr_b16 v[64:65],v0 offset:3072
	ds_read_b64_tr_b16 v[66:67],v0 offset:3584
	s_waitcnt lgkmcnt(0)
	s_nop 0
	v_mfma_f32_32x32x16_bf16 v[4:19], v[52:55], v[44:47], v[4:19]
	ds_read_b64_tr_b16 v[44:45],v0 offset:4096
	ds_read_b64_tr_b16 v[46:47],v0 offset:4608
	v_mfma_f32_32x32x16_bf16 v[4:19], v[56:59], v[48:51], v[4:19]
	ds_read_b64_tr_b16 v[48:49],v0 offset:5120
	ds_read_b64_tr_b16 v[50:51],v0 offset:5632
	v_mfma_f32_32x32x16_bf16 v[4:19], v[36:39], v[60:63], v[4:19]
	ds_read_b64_tr_b16 v[60:61],v0 offset:6144
	ds_read_b64_tr_b16 v[62:63],v0 offset:6656
	v_mfma_f32_32x32x16_bf16 v[4:19], v[40:43], v[64:67], v[4:19]
	ds_read_b64_tr_b16 v[64:65],v0 offset:7168
	ds_read_b64_tr_b16 v[66:67],v0 offset:7680
	s_waitcnt lgkmcnt(0)
	v_mfma_f32_32x32x16_bf16 v[20:35], v[52:55], v[44:47], v[20:35]
	v_mfma_f32_32x32x16_bf16 v[20:35], v[56:59], v[48:51], v[20:35]
	v_mfma_f32_32x32x16_bf16 v[20:35], v[36:39], v[60:63], v[20:35]
	v_mfma_f32_32x32x16_bf16 v[20:35], v[40:43], v[64:67], v[20:35]
	s_setprio 0
	v_mov_b32_e32 v0, v1
	s_nop 1
	v_permlane32_swap_b32_e32 v1, v0
	v_cmp_gt_u32_e32 vcc, 32, v186
	s_and_saveexec_b64 s[24:25], vcc
	s_cbranch_execz .LBB0_727
	v_lshl_add_u32 v3, v188, 2, s28
	v_add_f32_e32 v0, v1, v0
	ds_write_b32 v3, v0 offset:49280
	s_branch .LBB0_727
